# baseline (speedup 1.0000x reference)
;     __device__ __forceinline__ bf16_t* Wf2() const { return (bf16_t*)(ws + OFF_Wf2); }
;     __device__ __forceinline__ bf16_t* Act() const { return (bf16_t*)(ws + OFF_Act); }
; __global__ void __launch_bounds__(256, 2) fwd_kernel(Params p) {
;     ...
;             const int l = (ph - 1) >> 3, sp = (ph - 1) & 7;
;             if (sp == 0) {
;     ...
;             } else {
;                 for (int tile = bid; tile < 128 * 4; tile += nb) { const int x = tile & 7, q = tile >> 3; resid_big(pq, l, (q >> 2) * 8 + x, q & 3, pq.Act(), DFF, pq.Wf2() + (size_t)l * 1024 * DFF, 5120, false, smem); }
;                 for (int u = bid; u < 64; u += nb) resid_small(pq, l, u, pq.Act(), DFF, pq.Wf2() + (size_t)l * 1024 * DFF, 5120, smem);
.LBB0_15:
	v_writelane_b32 v254, s20, 8
	s_add_i32 s35, s82, -1
	s_ashr_i32 s4, s35, 3
	v_writelane_b32 v254, s21, 9
	v_writelane_b32 v254, s4, 10
	s_nop 1
	v_writelane_b32 v254, s5, 11
	s_and_b32 s4, s35, 7
	v_writelane_b32 v254, s4, 12
	v_writelane_b32 v254, s92, 13
	s_cmp_lt_i32 s4, 4
	s_mov_b64 s[4:5], -1
	v_writelane_b32 v254, s93, 14
	s_cbranch_scc1 .LBB0_101
	v_readlane_b32 s4, v254, 12
	s_cmp_lt_i32 s4, 6
	s_mov_b64 s[4:5], -1
	s_cbranch_scc1 .LBB0_40
	v_readlane_b32 s4, v254, 12
	s_cmp_gt_i32 s4, 6
	s_mov_b64 s[4:5], -1
	s_cbranch_scc0 .LBB0_29
	v_readlane_b32 s4, v254, 10
	s_cmpk_gt_i32 s78, 0x1ff
	s_mul_hi_i32 s10, s4, 0x580000
	s_mul_i32 s11, s4, 0x580000
	v_readlane_b32 s5, v254, 11
	s_cbranch_scc1 .LBB0_23
	s_cmpk_lt_i32 s78, 0x140
	s_cbranch_scc1 .Lstag_ffn2
	s_sleep 127
.Lstag_ffn2:
	v_readlane_b32 s2, v254, 1
	v_readlane_b32 s3, v254, 2
	s_add_u32 s12, s2, 0xb52c000
	s_addc_u32 s13, s3, 0
	s_add_u32 s4, s2, s11
	s_addc_u32 s5, s3, s10
	s_add_u32 s14, s4, 0x3500000
	s_addc_u32 s15, s5, 0
	v_readlane_b32 s6, v254, 10
	v_readlane_b32 s7, v254, 11
	s_mul_i32 s16, s6, 9
	s_add_u32 s6, s2, 0x4000000
	v_readlane_b32 s8, v254, 4
	s_addc_u32 s7, s3, 0
	s_lshl_b32 s17, s78, 5
	s_lshl_b32 s18, s8, 5
	s_mov_b32 s19, s78
	s_mov_b32 s20, s78
	v_readlane_b32 s9, v254, 5

;     __device__ __forceinline__ bf16_t* Wout() const { return (bf16_t*)(ws + OFF_Wout); }
;     __device__ __forceinline__ bf16_t* Mg() const { return (bf16_t*)(ws + OFF_Mg); }
; __global__ void __launch_bounds__(256, 2) fwd_kernel(Params p) {
;     ...
;             } else if (sp == 4) {
;                 for (int tile = bid; tile < 128 * 4; tile += nb) { const int x = tile & 7, q = tile >> 3; resid_big(pq, l, (q >> 2) * 8 + x, q & 3, pq.Mg(), 1024, pq.Wout() + (size_t)l * 1024 * 1024, 2048, true, smem); }
;                 for (int u = bid; u < 64; u += nb) resid_small(pq, l, u, pq.Mg(), 1024, pq.Wout() + (size_t)l * 1024 * 1024, 2048, smem);
.LBB0_58:
	s_andn2_b64 vcc, exec, s[4:5]
	s_cbranch_vccnz .LBB0_100
	s_cmpk_gt_i32 s78, 0x1ff
	s_movk_i32 s30, 0x2000
	s_cbranch_scc1 .LBB0_96
	s_cmpk_lt_i32 s78, 0x140
	s_cbranch_scc1 .Lstag_outp
	s_sleep 100
.Lstag_outp:
	v_readlane_b32 s2, v254, 1
	v_readlane_b32 s3, v254, 2
	s_add_u32 s16, s2, 0x60ac000
	v_readlane_b32 s0, v254, 10
	s_addc_u32 s17, s3, 0
	v_readlane_b32 s1, v254, 11
	s_mov_b32 s4, s0
	s_ashr_i32 s5, s0, 31
	s_lshl_b64 s[0:1], s[4:5], 21
	s_add_u32 s8, s2, s0
	s_addc_u32 s9, s3, s1
	s_add_u32 s18, s8, 0x1b00000
	s_mov_b32 s0, s4
	s_addc_u32 s19, s9, 0
	v_writelane_b32 v254, s0, 10
	s_cmp_gt_u32 s82, 8
	s_cselect_b64 s[10:11], -1, 0
	v_writelane_b32 v254, s1, 11
	s_add_u32 s12, s2, 0x4000000
	v_readlane_b32 s0, v254, 4
	s_mul_i32 s20, s4, 9
	s_addc_u32 s13, s3, 0
	s_lshl_b32 s21, s78, 5
	s_lshl_b32 s22, s0, 5
	s_mov_b32 s23, s78
	s_mov_b32 s28, s78
	v_readlane_b32 s1, v254, 5
	s_branch .LBB0_63
